# retention scan inner loop rewritten: 16 chunk loads per trip instead of 4 (same arithmetic), on top of flattened barrier
# baseline (speedup 1.0000x reference)
; DEV int tid_() { int t = threadIdx.x; asm volatile("" : "+v"(t)); return t; }
; DEV int bid_() { int t = blockIdx.x; asm volatile("" : "+s"(t)); return t; }
; DEV int gdim_() { int t = gridDim.x; asm volatile("" : "+s"(t)); return t; }
; #define P (*launderP(lp))
; DEV float log_sigmoid(float x) { return -log1pf(expf(-x)); }
; __device__ __forceinline__ void phase_scan(PREF P, int slab, u16* ST) {
;   const int Sshift = slab < 2 ? 12 : 13;
;   const int nseq = TS >> Sshift, nC = 1 << (Sshift - 7);
;   const int nitems = nseq * 16 * 4096;
;   for (int idx = bid_() * NTHR + tid_(); idx < nitems; idx += gdim_() * NTHR) {
;     const int e8 = idx & 4095, hd = (idx >> 12) & 15, seq = idx >> 16;
;     const int dir = hd & 1, h = hd >> 1;
;     const float dec = expf(log_sigmoid(P.decay_logit[dir * 8 + h]) * 128.f);
;     float R[8];
; #pragma unroll
;     for (int e = 0; e < 8; ++e) R[e] = 0.f;
;     u16* base = ST + (size_t)hd * 32768 + e8 * 8;
.LBB0_253:
	ds_read_b64 v[2:3], v20 offset:40
	v_lshrrev_b32_e32 v0, 11, v21
	v_bfe_u32 v1, v21, 12, 1
	v_and_b32_e32 v0, 28, v0
	v_lshl_or_b32 v180, v1, 5, v0
	s_waitcnt lgkmcnt(0)
	v_lshl_add_u64 v[2:3], v[2:3], 0, v[180:181]
	flat_load_dword v2, v[2:3]
	s_mov_b32 s19, 0x3f2aaaab
	s_mov_b32 s24, 0x3f317218
	v_lshlrev_b32_sdwa v22, s16, sext(v21) dst_sel:DWORD dst_unused:UNUSED_PAD src0_sel:DWORD src1_sel:WORD_1
	s_waitcnt vmcnt(0) lgkmcnt(0)
	v_mul_f32_e32 v0, 0xbfb8aa3b, v2
	v_fma_f32 v3, v2, s22, -v0
	v_rndne_f32_e32 v4, v0
	v_fmac_f32_e32 v3, 0xb2a5705f, v2
	v_sub_f32_e32 v0, v0, v4
	v_add_f32_e32 v0, v0, v3
	v_exp_f32_e32 v0, v0
	v_cvt_i32_f32_e32 v3, v4
	v_cmp_nlt_f32_e32 vcc, s23, v2
	v_ldexp_f32 v3, v0, v3
	s_nop 0
	v_cndmask_b32_e32 v3, 0, v3, vcc
	v_cmp_ngt_f32_e32 vcc, s20, v2
	v_mov_b32_e32 v0, 0
	v_mov_b32_e32 v16, v0
	v_cndmask_b32_e32 v4, v205, v3, vcc
	v_add_f32_e32 v5, 1.0, v4
	v_add_f32_e32 v2, -1.0, v5
	v_sub_f32_e32 v3, v2, v5
	v_add_f32_e32 v3, 1.0, v3
	v_sub_f32_e32 v2, v4, v2
	v_add_f32_e32 v6, v2, v3
	v_frexp_mant_f32_e32 v2, v5
	v_cmp_gt_f32_e32 vcc, s19, v2
	v_cvt_f64_f32_e32 v[2:3], v5
	v_frexp_exp_i32_f64_e32 v2, v[2:3]
	v_subbrev_co_u32_e32 v2, vcc, 0, v2, vcc
	v_sub_u32_e32 v3, 0, v2
	v_ldexp_f32 v5, v5, v3
	v_ldexp_f32 v3, v6, v3
	v_add_f32_e32 v6, -1.0, v5
	v_add_f32_e32 v7, 1.0, v6
	v_sub_f32_e32 v7, v5, v7
	v_add_f32_e32 v7, v3, v7
	v_add_f32_e32 v8, v6, v7
	v_sub_f32_e32 v6, v6, v8
	v_add_f32_e32 v6, v7, v6
	v_add_f32_e32 v7, 1.0, v5
	v_add_f32_e32 v9, -1.0, v7
	v_sub_f32_e32 v5, v5, v9
	v_add_f32_e32 v3, v3, v5
	v_add_f32_e32 v5, v7, v3
	v_sub_f32_e32 v7, v7, v5
	v_add_f32_e32 v3, v3, v7
	v_rcp_f32_e32 v7, v5
	v_cvt_f32_i32_e32 v2, v2
	s_mov_b32 s19, 0
	v_mov_b32_e32 v17, v0
	v_mul_f32_e32 v9, v8, v7
	v_mul_f32_e32 v10, v5, v9
	v_fma_f32 v11, v9, v5, -v10
	v_fmac_f32_e32 v11, v9, v3
	v_add_f32_e32 v12, v10, v11
	v_sub_f32_e32 v13, v8, v12
	v_sub_f32_e32 v8, v8, v13
	v_sub_f32_e32 v10, v12, v10
	v_sub_f32_e32 v8, v8, v12
	v_add_f32_e32 v6, v6, v8
	v_sub_f32_e32 v8, v10, v11
	v_add_f32_e32 v6, v8, v6
	v_add_f32_e32 v8, v13, v6
	v_mul_f32_e32 v10, v7, v8
	v_mul_f32_e32 v11, v5, v10
	v_fma_f32 v5, v10, v5, -v11
	v_fmac_f32_e32 v5, v10, v3
	v_sub_f32_e32 v3, v13, v8
	v_add_f32_e32 v3, v6, v3
	v_add_f32_e32 v6, v11, v5
	v_sub_f32_e32 v12, v8, v6
	v_sub_f32_e32 v8, v8, v12
	v_sub_f32_e32 v11, v6, v11
	v_sub_f32_e32 v6, v8, v6
	v_add_f32_e32 v3, v3, v6
	v_sub_f32_e32 v5, v11, v5
	v_add_f32_e32 v3, v5, v3
	v_add_f32_e32 v5, v9, v10
	v_add_f32_e32 v3, v12, v3
	v_sub_f32_e32 v6, v5, v9
	v_mul_f32_e32 v3, v7, v3
	v_sub_f32_e32 v6, v10, v6
	v_add_f32_e32 v3, v6, v3
	v_mul_f32_e32 v9, 0x3f317218, v2
	v_add_f32_e32 v6, v5, v3
	v_fma_f32 v10, v2, s24, -v9
	v_mul_f32_e32 v7, v6, v6
	v_fmac_f32_e32 v10, 0xb102e308, v2
	v_sub_f32_e32 v2, v6, v5
	v_fmamk_f32 v8, v7, 0x3e9b6dac, v192
	v_sub_f32_e32 v2, v3, v2
	v_add_f32_e32 v3, v9, v10
	v_fmaak_f32 v8, v7, v8, 0x3f2aaada
	v_sub_f32_e32 v5, v3, v9
	v_ldexp_f32 v9, v6, 1
	v_mul_f32_e32 v6, v6, v7
	v_mul_f32_e32 v6, v6, v8
	v_add_f32_e32 v7, v9, v6
	v_sub_f32_e32 v8, v7, v9
	v_ldexp_f32 v2, v2, 1
	v_sub_f32_e32 v6, v6, v8
	v_add_f32_e32 v2, v2, v6
	v_add_f32_e32 v6, v7, v2
	v_sub_f32_e32 v7, v6, v7
	v_sub_f32_e32 v2, v2, v7
	v_add_f32_e32 v7, v3, v6
	v_sub_f32_e32 v8, v7, v3
	v_sub_f32_e32 v9, v7, v8
	v_sub_f32_e32 v5, v10, v5
	v_sub_f32_e32 v3, v3, v9
	v_sub_f32_e32 v6, v6, v8
	v_add_f32_e32 v3, v6, v3
	v_add_f32_e32 v6, v5, v2
	v_sub_f32_e32 v8, v6, v5
	v_sub_f32_e32 v9, v6, v8
	v_sub_f32_e32 v5, v5, v9
	v_sub_f32_e32 v2, v2, v8
	v_add_f32_e32 v3, v6, v3
	v_add_f32_e32 v2, v2, v5
	v_add_f32_e32 v5, v7, v3
	v_sub_f32_e32 v6, v5, v7
	v_sub_f32_e32 v3, v3, v6
	v_add_f32_e32 v2, v2, v3
	s_mov_b32 s24, 0x7f800000
	v_add_f32_e32 v2, v5, v2
	v_cmp_neq_f32_e32 vcc, s24, v4
	s_mov_b32 s24, 0x33800000
	v_mov_b32_e32 v14, v0
	v_cndmask_b32_e32 v2, v205, v2, vcc
	v_cmp_lt_f32_e64 vcc, |v4|, s24
	s_mov_b32 s24, 0x3fb8aa3b
	v_mov_b32_e32 v15, v0
	v_cndmask_b32_e32 v2, v2, v4, vcc
	v_mul_f32_e32 v2, 0xc3000000, v2
	v_mul_f32_e32 v3, 0x3fb8aa3b, v2
	v_fma_f32 v4, v2, s24, -v3
	v_rndne_f32_e32 v5, v3
	v_fmac_f32_e32 v4, 0x32a5705f, v2
	v_sub_f32_e32 v3, v3, v5
	v_add_f32_e32 v3, v3, v4
	v_exp_f32_e32 v3, v3
	v_cvt_i32_f32_e32 v4, v5
	s_mov_b32 s24, 0xc2ce8ed0
	v_cmp_ngt_f32_e32 vcc, s24, v2
	s_mov_b32 s24, 0x42b17218
	v_ldexp_f32 v3, v3, v4
	v_cndmask_b32_e32 v3, 0, v3, vcc
	v_cmp_nlt_f32_e32 vcc, s24, v2
	s_mov_b32 s24, s18
	v_mov_b32_e32 v18, v0
	v_cndmask_b32_e32 v2, v205, v3, vcc
	v_lshlrev_b32_e32 v3, 4, v21
	v_and_b32_e32 v180, 0xf0000, v3
	v_lshl_add_u64 v[4:5], v[184:185], 0, v[180:181]
	v_and_b32_e32 v180, 0xfff0, v3
	v_lshl_add_u64 v[4:5], v[4:5], 0, v[180:181]
	v_cmp_eq_u32_e32 vcc, 0, v1
	v_mov_b32_e32 v3, v2
	v_mov_b32_e32 v6, v2
	v_mov_b32_e32 v7, v2
	v_mov_b32_e32 v8, v2
	v_mov_b32_e32 v9, v2
	v_mov_b32_e32 v10, v2
	v_mov_b32_e32 v11, v2
	v_mov_b32_e32 v12, v2
	v_mov_b32_e32 v13, v2
	v_mov_b32_e32 v1, v0
	v_mov_b32_e32 v19, v0
	s_add_i32 s36, s24, 3
	v_mov_b32_e32 v23, s36
	v_mov_b32_e32 v24, s19
	v_cndmask_b32_e32 v23, v23, v24, vcc
	v_add_u32_e32 v24, v23, v22
	v_ashrrev_i32_e32 v25, 31, v24
	v_lshlrev_b64 v[24:25], 20, v[24:25]
	v_lshl_add_u64 v[130:131], v[4:5], 0, v[24:25]
	v_mov_b32_e32 v162, 0xfff00000
	v_mov_b32_e32 v163, -1
	v_mov_b32_e32 v23, 0x100000
	v_cndmask_b32_e32 v162, v162, v23, vcc
	v_cndmask_b32_e64 v163, v163, 0, vcc
; DEV float bflo(unsigned u) { return __uint_as_float(u << 16); }
; DEV float bfhi(unsigned u) { return __uint_as_float(u & 0xffff0000u); }
; __device__ __forceinline__ void phase_scan(PREF P, int slab, u16* ST) {
;     ...
;     for (int cc = 0; cc < nC; cc += 4) {
;       uint4 v[4];
; #pragma unroll
;       for (int u = 0; u < 4; ++u) {
;         int c = dir == 0 ? (cc + u) : (nC - 1 - cc - u);
;         v[u] = *(const uint4*)(base + (size_t)(seq * nC + c) * (16 * 32768));
;       }
; #pragma unroll
;       for (int u = 0; u < 4; ++u) {
;         int c = dir == 0 ? (cc + u) : (nC - 1 - cc - u);
;         uint4 o;
;         o.x = pack2(R[0], R[1]); o.y = pack2(R[2], R[3]); o.z = pack2(R[4], R[5]); o.w = pack2(R[6], R[7]);
;         *(uint4*)(base + (size_t)(seq * nC + c) * (16 * 32768)) = o;
;         R[0] = R[0] * dec + bflo(v[u].x); R[1] = R[1] * dec + bfhi(v[u].x);
;         R[2] = R[2] * dec + bflo(v[u].y); R[3] = R[3] * dec + bfhi(v[u].y);
;         R[4] = R[4] * dec + bflo(v[u].z); R[5] = R[5] * dec + bfhi(v[u].z);
;         R[6] = R[6] * dec + bflo(v[u].w); R[7] = R[7] * dec + bfhi(v[u].w);
;       }
;     }
Lscan_loop:
	v_lshl_add_u64 v[132:133], v[130:131], 0, v[162:163]
	flat_load_dwordx4 v[66:69], v[130:131]
	flat_load_dwordx4 v[70:73], v[132:133]
	v_lshl_add_u64 v[134:135], v[132:133], 0, v[162:163]
	flat_load_dwordx4 v[74:77], v[134:135]
	v_lshl_add_u64 v[136:137], v[134:135], 0, v[162:163]
	flat_load_dwordx4 v[78:81], v[136:137]
	v_lshl_add_u64 v[138:139], v[136:137], 0, v[162:163]
	flat_load_dwordx4 v[82:85], v[138:139]
	v_lshl_add_u64 v[140:141], v[138:139], 0, v[162:163]
	flat_load_dwordx4 v[86:89], v[140:141]
	v_lshl_add_u64 v[142:143], v[140:141], 0, v[162:163]
	flat_load_dwordx4 v[90:93], v[142:143]
	v_lshl_add_u64 v[144:145], v[142:143], 0, v[162:163]
	flat_load_dwordx4 v[94:97], v[144:145]
	v_lshl_add_u64 v[146:147], v[144:145], 0, v[162:163]
	flat_load_dwordx4 v[98:101], v[146:147]
	v_lshl_add_u64 v[148:149], v[146:147], 0, v[162:163]
	flat_load_dwordx4 v[102:105], v[148:149]
	v_lshl_add_u64 v[150:151], v[148:149], 0, v[162:163]
	flat_load_dwordx4 v[106:109], v[150:151]
	v_lshl_add_u64 v[152:153], v[150:151], 0, v[162:163]
	flat_load_dwordx4 v[110:113], v[152:153]
	v_lshl_add_u64 v[154:155], v[152:153], 0, v[162:163]
	flat_load_dwordx4 v[114:117], v[154:155]
	v_lshl_add_u64 v[156:157], v[154:155], 0, v[162:163]
	flat_load_dwordx4 v[118:121], v[156:157]
	v_lshl_add_u64 v[158:159], v[156:157], 0, v[162:163]
	flat_load_dwordx4 v[122:125], v[158:159]
	v_lshl_add_u64 v[160:161], v[158:159], 0, v[162:163]
	flat_load_dwordx4 v[126:129], v[160:161]
	v_cvt_pk_bf16_f32 v222, v0, v1
	v_cvt_pk_bf16_f32 v223, v16, v17
	v_cvt_pk_bf16_f32 v224, v14, v15
	v_cvt_pk_bf16_f32 v225, v18, v19
	flat_store_dwordx4 v[130:131], v[222:225]
	s_add_i32 s19, s19, 16
	s_waitcnt vmcnt(0) lgkmcnt(0)
	v_lshlrev_b32_e32 v164, 16, v66
	v_and_b32_e32 v165, 0xffff0000, v66
	v_lshlrev_b32_e32 v166, 16, v67
	v_and_b32_e32 v167, 0xffff0000, v67
	v_lshlrev_b32_e32 v168, 16, v68
	v_and_b32_e32 v169, 0xffff0000, v68
	v_lshlrev_b32_e32 v170, 16, v69
	v_and_b32_e32 v171, 0xffff0000, v69
	v_fma_f32 v0, v2, v0, v164
	v_fma_f32 v1, v2, v1, v165
	v_fma_f32 v16, v2, v16, v166
	v_fma_f32 v17, v2, v17, v167
	v_fma_f32 v14, v2, v14, v168
	v_fma_f32 v15, v2, v15, v169
	v_fma_f32 v18, v2, v18, v170
	v_fma_f32 v19, v2, v19, v171
	v_cvt_pk_bf16_f32 v226, v0, v1
	v_cvt_pk_bf16_f32 v227, v16, v17
	v_cvt_pk_bf16_f32 v228, v14, v15
	v_cvt_pk_bf16_f32 v229, v18, v19
	flat_store_dwordx4 v[132:133], v[226:229]
	v_lshlrev_b32_e32 v164, 16, v70
	v_and_b32_e32 v165, 0xffff0000, v70
	v_lshlrev_b32_e32 v166, 16, v71
	v_and_b32_e32 v167, 0xffff0000, v71
	v_lshlrev_b32_e32 v168, 16, v72
	v_and_b32_e32 v169, 0xffff0000, v72
	v_lshlrev_b32_e32 v170, 16, v73
	v_and_b32_e32 v171, 0xffff0000, v73
	v_fma_f32 v0, v2, v0, v164
	v_fma_f32 v1, v2, v1, v165
	v_fma_f32 v16, v2, v16, v166
	v_fma_f32 v17, v2, v17, v167
	v_fma_f32 v14, v2, v14, v168
	v_fma_f32 v15, v2, v15, v169
	v_fma_f32 v18, v2, v18, v170
	v_fma_f32 v19, v2, v19, v171
	v_cvt_pk_bf16_f32 v222, v0, v1
	v_cvt_pk_bf16_f32 v223, v16, v17
	v_cvt_pk_bf16_f32 v224, v14, v15
	v_cvt_pk_bf16_f32 v225, v18, v19
	flat_store_dwordx4 v[134:135], v[222:225]
	v_lshlrev_b32_e32 v164, 16, v74
	v_and_b32_e32 v165, 0xffff0000, v74
	v_lshlrev_b32_e32 v166, 16, v75
	v_and_b32_e32 v167, 0xffff0000, v75
	v_lshlrev_b32_e32 v168, 16, v76
	v_and_b32_e32 v169, 0xffff0000, v76
	v_lshlrev_b32_e32 v170, 16, v77
	v_and_b32_e32 v171, 0xffff0000, v77
	v_fma_f32 v0, v2, v0, v164
	v_fma_f32 v1, v2, v1, v165
	v_fma_f32 v16, v2, v16, v166
	v_fma_f32 v17, v2, v17, v167
	v_fma_f32 v14, v2, v14, v168
	v_fma_f32 v15, v2, v15, v169
	v_fma_f32 v18, v2, v18, v170
	v_fma_f32 v19, v2, v19, v171
	v_cvt_pk_bf16_f32 v226, v0, v1
	v_cvt_pk_bf16_f32 v227, v16, v17
	v_cvt_pk_bf16_f32 v228, v14, v15
	v_cvt_pk_bf16_f32 v229, v18, v19
	flat_store_dwordx4 v[136:137], v[226:229]
	v_lshlrev_b32_e32 v164, 16, v78
	v_and_b32_e32 v165, 0xffff0000, v78
	v_lshlrev_b32_e32 v166, 16, v79
	v_and_b32_e32 v167, 0xffff0000, v79
	v_lshlrev_b32_e32 v168, 16, v80
	v_and_b32_e32 v169, 0xffff0000, v80
	v_lshlrev_b32_e32 v170, 16, v81
	v_and_b32_e32 v171, 0xffff0000, v81
	v_fma_f32 v0, v2, v0, v164
	v_fma_f32 v1, v2, v1, v165
	v_fma_f32 v16, v2, v16, v166
	v_fma_f32 v17, v2, v17, v167
	v_fma_f32 v14, v2, v14, v168
	v_fma_f32 v15, v2, v15, v169
	v_fma_f32 v18, v2, v18, v170
	v_fma_f32 v19, v2, v19, v171
	v_cvt_pk_bf16_f32 v222, v0, v1
	v_cvt_pk_bf16_f32 v223, v16, v17
	v_cvt_pk_bf16_f32 v224, v14, v15
	v_cvt_pk_bf16_f32 v225, v18, v19
	flat_store_dwordx4 v[138:139], v[222:225]
	v_lshlrev_b32_e32 v164, 16, v82
	v_and_b32_e32 v165, 0xffff0000, v82
	v_lshlrev_b32_e32 v166, 16, v83
	v_and_b32_e32 v167, 0xffff0000, v83
	v_lshlrev_b32_e32 v168, 16, v84
	v_and_b32_e32 v169, 0xffff0000, v84
	v_lshlrev_b32_e32 v170, 16, v85
	v_and_b32_e32 v171, 0xffff0000, v85
	v_fma_f32 v0, v2, v0, v164
	v_fma_f32 v1, v2, v1, v165
	v_fma_f32 v16, v2, v16, v166
	v_fma_f32 v17, v2, v17, v167
	v_fma_f32 v14, v2, v14, v168
	v_fma_f32 v15, v2, v15, v169
	v_fma_f32 v18, v2, v18, v170
	v_fma_f32 v19, v2, v19, v171
	v_cvt_pk_bf16_f32 v226, v0, v1
	v_cvt_pk_bf16_f32 v227, v16, v17
	v_cvt_pk_bf16_f32 v228, v14, v15
	v_cvt_pk_bf16_f32 v229, v18, v19
	flat_store_dwordx4 v[140:141], v[226:229]
	v_lshlrev_b32_e32 v164, 16, v86
	v_and_b32_e32 v165, 0xffff0000, v86
	v_lshlrev_b32_e32 v166, 16, v87
	v_and_b32_e32 v167, 0xffff0000, v87
	v_lshlrev_b32_e32 v168, 16, v88
	v_and_b32_e32 v169, 0xffff0000, v88
	v_lshlrev_b32_e32 v170, 16, v89
	v_and_b32_e32 v171, 0xffff0000, v89
	v_fma_f32 v0, v2, v0, v164
	v_fma_f32 v1, v2, v1, v165
	v_fma_f32 v16, v2, v16, v166
	v_fma_f32 v17, v2, v17, v167
	v_fma_f32 v14, v2, v14, v168
	v_fma_f32 v15, v2, v15, v169
; DEV float bflo(unsigned u) { return __uint_as_float(u << 16); }
; DEV float bfhi(unsigned u) { return __uint_as_float(u & 0xffff0000u); }
; __device__ __forceinline__ void phase_scan(PREF P, int slab, u16* ST) {
;     ...
;     for (int cc = 0; cc < nC; cc += 4) {
;       uint4 v[4];
; #pragma unroll
;       for (int u = 0; u < 4; ++u) {
;         int c = dir == 0 ? (cc + u) : (nC - 1 - cc - u);
;         v[u] = *(const uint4*)(base + (size_t)(seq * nC + c) * (16 * 32768));
;       }
; #pragma unroll
;       for (int u = 0; u < 4; ++u) {
;         int c = dir == 0 ? (cc + u) : (nC - 1 - cc - u);
;         uint4 o;
;         o.x = pack2(R[0], R[1]); o.y = pack2(R[2], R[3]); o.z = pack2(R[4], R[5]); o.w = pack2(R[6], R[7]);
;         *(uint4*)(base + (size_t)(seq * nC + c) * (16 * 32768)) = o;
;         R[0] = R[0] * dec + bflo(v[u].x); R[1] = R[1] * dec + bfhi(v[u].x);
;         R[2] = R[2] * dec + bflo(v[u].y); R[3] = R[3] * dec + bfhi(v[u].y);
;         R[4] = R[4] * dec + bflo(v[u].z); R[5] = R[5] * dec + bfhi(v[u].z);
;         R[6] = R[6] * dec + bflo(v[u].w); R[7] = R[7] * dec + bfhi(v[u].w);
;       }
;     }
	v_fma_f32 v18, v2, v18, v170
	v_fma_f32 v19, v2, v19, v171
	v_cvt_pk_bf16_f32 v222, v0, v1
	v_cvt_pk_bf16_f32 v223, v16, v17
	v_cvt_pk_bf16_f32 v224, v14, v15
	v_cvt_pk_bf16_f32 v225, v18, v19
	flat_store_dwordx4 v[142:143], v[222:225]
	v_lshlrev_b32_e32 v164, 16, v90
	v_and_b32_e32 v165, 0xffff0000, v90
	v_lshlrev_b32_e32 v166, 16, v91
	v_and_b32_e32 v167, 0xffff0000, v91
	v_lshlrev_b32_e32 v168, 16, v92
	v_and_b32_e32 v169, 0xffff0000, v92
	v_lshlrev_b32_e32 v170, 16, v93
	v_and_b32_e32 v171, 0xffff0000, v93
	v_fma_f32 v0, v2, v0, v164
	v_fma_f32 v1, v2, v1, v165
	v_fma_f32 v16, v2, v16, v166
	v_fma_f32 v17, v2, v17, v167
	v_fma_f32 v14, v2, v14, v168
	v_fma_f32 v15, v2, v15, v169
	v_fma_f32 v18, v2, v18, v170
	v_fma_f32 v19, v2, v19, v171
	v_cvt_pk_bf16_f32 v226, v0, v1
	v_cvt_pk_bf16_f32 v227, v16, v17
	v_cvt_pk_bf16_f32 v228, v14, v15
	v_cvt_pk_bf16_f32 v229, v18, v19
	flat_store_dwordx4 v[144:145], v[226:229]
	v_lshlrev_b32_e32 v164, 16, v94
	v_and_b32_e32 v165, 0xffff0000, v94
	v_lshlrev_b32_e32 v166, 16, v95
	v_and_b32_e32 v167, 0xffff0000, v95
	v_lshlrev_b32_e32 v168, 16, v96
	v_and_b32_e32 v169, 0xffff0000, v96
	v_lshlrev_b32_e32 v170, 16, v97
	v_and_b32_e32 v171, 0xffff0000, v97
	v_fma_f32 v0, v2, v0, v164
	v_fma_f32 v1, v2, v1, v165
	v_fma_f32 v16, v2, v16, v166
	v_fma_f32 v17, v2, v17, v167
	v_fma_f32 v14, v2, v14, v168
	v_fma_f32 v15, v2, v15, v169
	v_fma_f32 v18, v2, v18, v170
	v_fma_f32 v19, v2, v19, v171
	v_cvt_pk_bf16_f32 v222, v0, v1
	v_cvt_pk_bf16_f32 v223, v16, v17
	v_cvt_pk_bf16_f32 v224, v14, v15
	v_cvt_pk_bf16_f32 v225, v18, v19
	flat_store_dwordx4 v[146:147], v[222:225]
	v_lshlrev_b32_e32 v164, 16, v98
	v_and_b32_e32 v165, 0xffff0000, v98
	v_lshlrev_b32_e32 v166, 16, v99
	v_and_b32_e32 v167, 0xffff0000, v99
	v_lshlrev_b32_e32 v168, 16, v100
	v_and_b32_e32 v169, 0xffff0000, v100
	v_lshlrev_b32_e32 v170, 16, v101
	v_and_b32_e32 v171, 0xffff0000, v101
	v_fma_f32 v0, v2, v0, v164
	v_fma_f32 v1, v2, v1, v165
	v_fma_f32 v16, v2, v16, v166
	v_fma_f32 v17, v2, v17, v167
	v_fma_f32 v14, v2, v14, v168
	v_fma_f32 v15, v2, v15, v169
	v_fma_f32 v18, v2, v18, v170
	v_fma_f32 v19, v2, v19, v171
	v_cvt_pk_bf16_f32 v226, v0, v1
	v_cvt_pk_bf16_f32 v227, v16, v17
	v_cvt_pk_bf16_f32 v228, v14, v15
	v_cvt_pk_bf16_f32 v229, v18, v19
	flat_store_dwordx4 v[148:149], v[226:229]
	v_lshlrev_b32_e32 v164, 16, v102
	v_and_b32_e32 v165, 0xffff0000, v102
	v_lshlrev_b32_e32 v166, 16, v103
	v_and_b32_e32 v167, 0xffff0000, v103
	v_lshlrev_b32_e32 v168, 16, v104
	v_and_b32_e32 v169, 0xffff0000, v104
	v_lshlrev_b32_e32 v170, 16, v105
	v_and_b32_e32 v171, 0xffff0000, v105
	v_fma_f32 v0, v2, v0, v164
	v_fma_f32 v1, v2, v1, v165
	v_fma_f32 v16, v2, v16, v166
	v_fma_f32 v17, v2, v17, v167
	v_fma_f32 v14, v2, v14, v168
	v_fma_f32 v15, v2, v15, v169
	v_fma_f32 v18, v2, v18, v170
	v_fma_f32 v19, v2, v19, v171
	v_cvt_pk_bf16_f32 v222, v0, v1
	v_cvt_pk_bf16_f32 v223, v16, v17
	v_cvt_pk_bf16_f32 v224, v14, v15
	v_cvt_pk_bf16_f32 v225, v18, v19
	flat_store_dwordx4 v[150:151], v[222:225]
	v_lshlrev_b32_e32 v164, 16, v106
	v_and_b32_e32 v165, 0xffff0000, v106
	v_lshlrev_b32_e32 v166, 16, v107
	v_and_b32_e32 v167, 0xffff0000, v107
	v_lshlrev_b32_e32 v168, 16, v108
	v_and_b32_e32 v169, 0xffff0000, v108
	v_lshlrev_b32_e32 v170, 16, v109
	v_and_b32_e32 v171, 0xffff0000, v109
	v_fma_f32 v0, v2, v0, v164
	v_fma_f32 v1, v2, v1, v165
	v_fma_f32 v16, v2, v16, v166
	v_fma_f32 v17, v2, v17, v167
	v_fma_f32 v14, v2, v14, v168
	v_fma_f32 v15, v2, v15, v169
	v_fma_f32 v18, v2, v18, v170
	v_fma_f32 v19, v2, v19, v171
	v_cvt_pk_bf16_f32 v226, v0, v1
	v_cvt_pk_bf16_f32 v227, v16, v17
	v_cvt_pk_bf16_f32 v228, v14, v15
	v_cvt_pk_bf16_f32 v229, v18, v19
; DEV float bflo(unsigned u) { return __uint_as_float(u << 16); }
; DEV float bfhi(unsigned u) { return __uint_as_float(u & 0xffff0000u); }
; __device__ __forceinline__ void phase_scan(PREF P, int slab, u16* ST) {
;     ...
;     for (int cc = 0; cc < nC; cc += 4) {
;       uint4 v[4];
; #pragma unroll
;       for (int u = 0; u < 4; ++u) {
;         int c = dir == 0 ? (cc + u) : (nC - 1 - cc - u);
;         v[u] = *(const uint4*)(base + (size_t)(seq * nC + c) * (16 * 32768));
;       }
; #pragma unroll
;       for (int u = 0; u < 4; ++u) {
;         int c = dir == 0 ? (cc + u) : (nC - 1 - cc - u);
;         uint4 o;
;         o.x = pack2(R[0], R[1]); o.y = pack2(R[2], R[3]); o.z = pack2(R[4], R[5]); o.w = pack2(R[6], R[7]);
;         *(uint4*)(base + (size_t)(seq * nC + c) * (16 * 32768)) = o;
;         R[0] = R[0] * dec + bflo(v[u].x); R[1] = R[1] * dec + bfhi(v[u].x);
;         R[2] = R[2] * dec + bflo(v[u].y); R[3] = R[3] * dec + bfhi(v[u].y);
;         R[4] = R[4] * dec + bflo(v[u].z); R[5] = R[5] * dec + bfhi(v[u].z);
;         R[6] = R[6] * dec + bflo(v[u].w); R[7] = R[7] * dec + bfhi(v[u].w);
;       }
;     }
	flat_store_dwordx4 v[152:153], v[226:229]
	v_lshlrev_b32_e32 v164, 16, v110
	v_and_b32_e32 v165, 0xffff0000, v110
	v_lshlrev_b32_e32 v166, 16, v111
	v_and_b32_e32 v167, 0xffff0000, v111
	v_lshlrev_b32_e32 v168, 16, v112
	v_and_b32_e32 v169, 0xffff0000, v112
	v_lshlrev_b32_e32 v170, 16, v113
	v_and_b32_e32 v171, 0xffff0000, v113
	v_fma_f32 v0, v2, v0, v164
	v_fma_f32 v1, v2, v1, v165
	v_fma_f32 v16, v2, v16, v166
	v_fma_f32 v17, v2, v17, v167
	v_fma_f32 v14, v2, v14, v168
	v_fma_f32 v15, v2, v15, v169
	v_fma_f32 v18, v2, v18, v170
	v_fma_f32 v19, v2, v19, v171
	v_cvt_pk_bf16_f32 v222, v0, v1
	v_cvt_pk_bf16_f32 v223, v16, v17
	v_cvt_pk_bf16_f32 v224, v14, v15
	v_cvt_pk_bf16_f32 v225, v18, v19
	flat_store_dwordx4 v[154:155], v[222:225]
	v_lshlrev_b32_e32 v164, 16, v114
	v_and_b32_e32 v165, 0xffff0000, v114
	v_lshlrev_b32_e32 v166, 16, v115
	v_and_b32_e32 v167, 0xffff0000, v115
	v_lshlrev_b32_e32 v168, 16, v116
	v_and_b32_e32 v169, 0xffff0000, v116
	v_lshlrev_b32_e32 v170, 16, v117
	v_and_b32_e32 v171, 0xffff0000, v117
	v_fma_f32 v0, v2, v0, v164
	v_fma_f32 v1, v2, v1, v165
	v_fma_f32 v16, v2, v16, v166
	v_fma_f32 v17, v2, v17, v167
	v_fma_f32 v14, v2, v14, v168
	v_fma_f32 v15, v2, v15, v169
	v_fma_f32 v18, v2, v18, v170
	v_fma_f32 v19, v2, v19, v171
	v_cvt_pk_bf16_f32 v226, v0, v1
	v_cvt_pk_bf16_f32 v227, v16, v17
	v_cvt_pk_bf16_f32 v228, v14, v15
	v_cvt_pk_bf16_f32 v229, v18, v19
	flat_store_dwordx4 v[156:157], v[226:229]
	v_lshlrev_b32_e32 v164, 16, v118
	v_and_b32_e32 v165, 0xffff0000, v118
	v_lshlrev_b32_e32 v166, 16, v119
	v_and_b32_e32 v167, 0xffff0000, v119
	v_lshlrev_b32_e32 v168, 16, v120
	v_and_b32_e32 v169, 0xffff0000, v120
	v_lshlrev_b32_e32 v170, 16, v121
	v_and_b32_e32 v171, 0xffff0000, v121
	v_fma_f32 v0, v2, v0, v164
	v_fma_f32 v1, v2, v1, v165
	v_fma_f32 v16, v2, v16, v166
	v_fma_f32 v17, v2, v17, v167
	v_fma_f32 v14, v2, v14, v168
	v_fma_f32 v15, v2, v15, v169
	v_fma_f32 v18, v2, v18, v170
	v_fma_f32 v19, v2, v19, v171
	v_cvt_pk_bf16_f32 v222, v0, v1
	v_cvt_pk_bf16_f32 v223, v16, v17
	v_cvt_pk_bf16_f32 v224, v14, v15
	v_cvt_pk_bf16_f32 v225, v18, v19
	flat_store_dwordx4 v[158:159], v[222:225]
	v_lshlrev_b32_e32 v164, 16, v122
	v_and_b32_e32 v165, 0xffff0000, v122
	v_lshlrev_b32_e32 v166, 16, v123
	v_and_b32_e32 v167, 0xffff0000, v123
	v_lshlrev_b32_e32 v168, 16, v124
	v_and_b32_e32 v169, 0xffff0000, v124
	v_lshlrev_b32_e32 v170, 16, v125
	v_and_b32_e32 v171, 0xffff0000, v125
	v_fma_f32 v0, v2, v0, v164
	v_fma_f32 v1, v2, v1, v165
	v_fma_f32 v16, v2, v16, v166
	v_fma_f32 v17, v2, v17, v167
	v_fma_f32 v14, v2, v14, v168
	v_fma_f32 v15, v2, v15, v169
	v_fma_f32 v18, v2, v18, v170
	v_fma_f32 v19, v2, v19, v171
	v_cvt_pk_bf16_f32 v226, v0, v1
	v_cvt_pk_bf16_f32 v227, v16, v17
	v_cvt_pk_bf16_f32 v228, v14, v15
	v_cvt_pk_bf16_f32 v229, v18, v19
	flat_store_dwordx4 v[160:161], v[226:229]
	v_lshlrev_b32_e32 v164, 16, v126
	v_and_b32_e32 v165, 0xffff0000, v126
	v_lshlrev_b32_e32 v166, 16, v127
	v_and_b32_e32 v167, 0xffff0000, v127
	v_lshlrev_b32_e32 v168, 16, v128
	v_and_b32_e32 v169, 0xffff0000, v128
	v_lshlrev_b32_e32 v170, 16, v129
	v_and_b32_e32 v171, 0xffff0000, v129
	v_fma_f32 v0, v2, v0, v164
	v_fma_f32 v1, v2, v1, v165
	v_fma_f32 v16, v2, v16, v166
	v_fma_f32 v17, v2, v17, v167
	v_fma_f32 v14, v2, v14, v168
	v_fma_f32 v15, v2, v15, v169
	v_fma_f32 v18, v2, v18, v170
	v_fma_f32 v19, v2, v19, v171
	v_lshl_add_u64 v[130:131], v[160:161], 0, v[162:163]
	s_cmp_ge_u32 s19, s17
	s_cbranch_scc0 Lscan_loop
	v_readlane_b32 s36, v251, 6
	s_mov_b32 s19, s36
	v_readlane_b32 s37, v251, 7
	v_lshl_add_u32 v21, s19, 8, v21
	v_cmp_le_i32_e32 vcc, s6, v21
	s_or_b64 s[14:15], vcc, s[14:15]
	s_andn2_b64 exec, exec, s[14:15]
	s_cbranch_execnz .LBB0_253
